# GLA V-tile prefetch: 12 two-byte loads per thread replaced by 6 dword loads (two adjacent columns per thread), LDS transpose writes use b16 + b16_d16_hi; latch waits recounted
# baseline (speedup 1.0000x reference)
.LBB0_533:
	s_or_b64 exec, exec, s[10:11]
	v_cmp_gt_i32_e32 vcc, 64, v2
	v_lshlrev_b32_e32 v129, 2, v2
	s_and_saveexec_b64 s[10:11], vcc
	ds_write_b32 v129, v179 offset:23552
	s_or_b64 exec, exec, s[10:11]
	s_add_u32 s58, s2, 0x22622100
	s_addc_u32 s59, s3, 0
	s_ashr_i32 s54, s95, 2
	v_lshlrev_b32_e32 v25, 3, v8
	s_add_u32 s56, s2, 0x18e80000
	v_and_b32_e32 v3, 24, v25
	s_addc_u32 s57, s3, 0
	s_ashr_i32 s55, s54, 31
	v_mul_u32_u24_e32 v3, 0x480, v3
	s_mul_i32 s10, s54, 0x480000
	v_add3_u32 v178, v0, s5, v3
	s_mul_hi_i32 s5, s54, 0x480000
	s_add_u32 s12, s58, s10
	s_addc_u32 s13, s59, s5
	v_lshl_add_u64 v[4:5], v[178:179], 1, s[12:13]
	v_add_u32_e32 v72, 0xc0, v178
	v_mov_b32_e32 v73, v179
	v_add_u32_e32 v74, 0x480, v178
	v_mov_b32_e32 v75, v179
	v_add_u32_e32 v76, 0x540, v178
	v_mov_b32_e32 v77, v179
	v_add_u32_e32 v78, 0x900, v178
	v_mov_b32_e32 v79, v179
	v_add_u32_e32 v80, 0x9c0, v178
	v_mov_b32_e32 v81, v179
	v_add_u32_e32 v82, 0xd80, v178
	v_mov_b32_e32 v83, v179
	v_add_u32_e32 v84, 0xe40, v178
	v_mov_b32_e32 v85, v179
	v_add_u32_e32 v86, 0x1200, v178
	v_mov_b32_e32 v87, v179
	v_mul_hi_u32 v3, v2, s87
	v_lshl_add_u64 v[6:7], v[72:73], 1, s[12:13]
	v_lshl_add_u64 v[12:13], v[74:75], 1, s[12:13]
	v_lshl_add_u64 v[14:15], v[76:77], 1, s[12:13]
	v_lshl_add_u64 v[16:17], v[78:79], 1, s[12:13]
	v_lshl_add_u64 v[18:19], v[80:81], 1, s[12:13]
	v_lshl_add_u64 v[20:21], v[82:83], 1, s[12:13]
	v_lshl_add_u64 v[22:23], v[84:85], 1, s[12:13]
	global_load_ushort v26, v[4:5], off
	global_load_ushort v143, v[6:7], off
	global_load_ushort v27, v[12:13], off
	global_load_ushort v140, v[14:15], off
	global_load_ushort v28, v[16:17], off
	global_load_ushort v136, v[18:19], off
	global_load_ushort v29, v[20:21], off
	global_load_ushort v138, v[22:23], off
	v_lshl_add_u64 v[4:5], v[86:87], 1, s[12:13]
	v_add_u32_e32 v88, 0x12c0, v178
	v_mov_b32_e32 v89, v179
	v_add_u32_e32 v90, 0x1680, v178
	v_mov_b32_e32 v91, v179
	v_add_u32_e32 v92, 0x1740, v178
	v_mov_b32_e32 v93, v179
	v_add_u32_e32 v94, 0x1b00, v178
	v_mov_b32_e32 v95, v179
	v_add_u32_e32 v96, 0x1bc0, v178
	v_mov_b32_e32 v97, v179
	v_add_u32_e32 v98, 0x1f80, v178
	v_mov_b32_e32 v99, v179
	v_add_u32_e32 v100, 0x2040, v178
	v_mov_b32_e32 v101, v179
	v_lshrrev_b32_e32 v3, 6, v3
	v_lshl_add_u64 v[6:7], v[88:89], 1, s[12:13]
	v_lshl_add_u64 v[12:13], v[90:91], 1, s[12:13]
	v_lshl_add_u64 v[14:15], v[92:93], 1, s[12:13]
	v_lshl_add_u64 v[16:17], v[94:95], 1, s[12:13]
	v_lshl_add_u64 v[18:19], v[96:97], 1, s[12:13]
	v_lshl_add_u64 v[20:21], v[98:99], 1, s[12:13]
	v_lshl_add_u64 v[22:23], v[100:101], 1, s[12:13]
	global_load_ushort v30, v[4:5], off
	global_load_ushort v144, v[6:7], off
	global_load_ushort v31, v[12:13], off
	global_load_ushort v142, v[14:15], off
	global_load_ushort v32, v[16:17], off
	global_load_ushort v137, v[18:19], off
	global_load_ushort v33, v[20:21], off
	global_load_ushort v139, v[22:23], off
	s_mul_i32 s5, s4, 0x60
	v_mul_lo_u32 v4, v3, s86
	v_mul_lo_u32 v3, v3, s75
	s_addk_i32 s5, 0x180
	v_sub_u32_e32 v3, v2, v3
	v_add_u32_e32 v34, 0x100, v2
	v_add3_u32 v102, v3, s5, v4
	v_lshlrev_b32_e32 v203, 1, v2
	v_lshrrev_b32_e32 v226, 5, v203
	v_mul_u32_u24_e32 v226, 0xaaab, v226
	v_lshrrev_b32_e32 v226, 17, v226
	v_mul_u32_u24_e32 v227, 0x60, v226
	v_sub_u32_e32 v227, v203, v227
	v_mul_u32_u24_e32 v252, 0x480, v226
	v_add3_u32 v252, v252, s5, v227
	v_lshlrev_b32_e32 v240, 1, v252
	v_and_b32_e32 v203, 4, v226
	v_lshlrev_b32_e32 v203, 1, v203
	v_and_b32_e32 v252, 8, v226
	v_lshrrev_b32_e32 v252, 1, v252
	v_and_b32_e32 v253, 0xfffffff3, v226
	v_or3_b32 v253, v253, v203, v252
	v_mul_u32_u24_e32 v203, 0x50, v227
	v_lshl_add_u32 v246, v253, 1, v203
	global_load_dword v181, v240, s[12:13]
	v_lshlrev_b32_e32 v203, 1, v2
	v_add_u32_e32 v203, 0x200, v203
	v_lshrrev_b32_e32 v226, 5, v203
	v_mul_u32_u24_e32 v226, 0xaaab, v226
	v_lshrrev_b32_e32 v226, 17, v226
	v_mul_u32_u24_e32 v227, 0x60, v226
	v_sub_u32_e32 v227, v203, v227
	v_mul_u32_u24_e32 v252, 0x480, v226
	v_add3_u32 v252, v252, s5, v227
	v_lshlrev_b32_e32 v241, 1, v252
	v_and_b32_e32 v203, 4, v226
	v_lshlrev_b32_e32 v203, 1, v203
	v_and_b32_e32 v252, 8, v226
	v_lshrrev_b32_e32 v252, 1, v252
	v_and_b32_e32 v253, 0xfffffff3, v226
	v_or3_b32 v253, v253, v203, v252
	v_mul_u32_u24_e32 v203, 0x50, v227
	v_lshl_add_u32 v247, v253, 1, v203
	global_load_dword v182, v241, s[12:13]
	v_lshlrev_b32_e32 v203, 1, v2
	v_add_u32_e32 v203, 0x400, v203
	v_lshrrev_b32_e32 v226, 5, v203
	v_mul_u32_u24_e32 v226, 0xaaab, v226
	v_lshrrev_b32_e32 v226, 17, v226
	v_mul_u32_u24_e32 v227, 0x60, v226
	v_sub_u32_e32 v227, v203, v227
	v_mul_u32_u24_e32 v252, 0x480, v226
	v_add3_u32 v252, v252, s5, v227
	v_lshlrev_b32_e32 v242, 1, v252
	v_and_b32_e32 v203, 4, v226
	v_lshlrev_b32_e32 v203, 1, v203
	v_and_b32_e32 v252, 8, v226
	v_lshrrev_b32_e32 v252, 1, v252
	v_and_b32_e32 v253, 0xfffffff3, v226
	v_or3_b32 v253, v253, v203, v252
	v_mul_u32_u24_e32 v203, 0x50, v227
	v_lshl_add_u32 v248, v253, 1, v203
	global_load_dword v183, v242, s[12:13]
	v_lshlrev_b32_e32 v203, 1, v2
	v_add_u32_e32 v203, 0x600, v203
	v_lshrrev_b32_e32 v226, 5, v203
	v_mul_u32_u24_e32 v226, 0xaaab, v226
	v_lshrrev_b32_e32 v226, 17, v226
	v_mul_u32_u24_e32 v227, 0x60, v226
	v_sub_u32_e32 v227, v203, v227
	v_mul_u32_u24_e32 v252, 0x480, v226
	v_add3_u32 v252, v252, s5, v227
	v_lshlrev_b32_e32 v243, 1, v252
	v_and_b32_e32 v203, 4, v226
	v_lshlrev_b32_e32 v203, 1, v203
	v_and_b32_e32 v252, 8, v226
	v_lshrrev_b32_e32 v252, 1, v252
	v_and_b32_e32 v253, 0xfffffff3, v226
	v_or3_b32 v253, v253, v203, v252
	v_mul_u32_u24_e32 v203, 0x50, v227
	v_lshl_add_u32 v249, v253, 1, v203
	global_load_dword v184, v243, s[12:13]
	v_lshlrev_b32_e32 v203, 1, v2
	v_add_u32_e32 v203, 0x800, v203
	v_lshrrev_b32_e32 v226, 5, v203
	v_mul_u32_u24_e32 v226, 0xaaab, v226
	v_lshrrev_b32_e32 v226, 17, v226
	v_mul_u32_u24_e32 v227, 0x60, v226
	v_sub_u32_e32 v227, v203, v227
	v_mul_u32_u24_e32 v252, 0x480, v226
	v_add3_u32 v252, v252, s5, v227
	v_lshlrev_b32_e32 v244, 1, v252
	v_and_b32_e32 v203, 4, v226
	v_lshlrev_b32_e32 v203, 1, v203
	v_and_b32_e32 v252, 8, v226
	v_lshrrev_b32_e32 v252, 1, v252
	v_and_b32_e32 v253, 0xfffffff3, v226
	v_or3_b32 v253, v253, v203, v252
	v_mul_u32_u24_e32 v203, 0x50, v227
	v_lshl_add_u32 v250, v253, 1, v203
	global_load_dword v185, v244, s[12:13]
	v_lshlrev_b32_e32 v203, 1, v2
	v_add_u32_e32 v203, 0xa00, v203
	v_lshrrev_b32_e32 v226, 5, v203
	v_mul_u32_u24_e32 v226, 0xaaab, v226
	v_lshrrev_b32_e32 v226, 17, v226
	v_mul_u32_u24_e32 v227, 0x60, v226
	v_sub_u32_e32 v227, v203, v227
	v_mul_u32_u24_e32 v252, 0x480, v226
	v_add3_u32 v252, v252, s5, v227
	v_lshlrev_b32_e32 v245, 1, v252
	v_and_b32_e32 v203, 4, v226
	v_lshlrev_b32_e32 v203, 1, v203
	v_and_b32_e32 v252, 8, v226
	v_lshrrev_b32_e32 v252, 1, v252
	v_and_b32_e32 v253, 0xfffffff3, v226
	v_or3_b32 v253, v253, v203, v252
	v_mul_u32_u24_e32 v203, 0x50, v227
	v_lshl_add_u32 v251, v253, 1, v203
	global_load_dword v186, v245, s[12:13]
	v_mul_hi_u32 v3, v34, s87
	v_lshrrev_b32_e32 v3, 6, v3
	v_mul_lo_u32 v6, v3, s86
	v_mul_lo_u32 v3, v3, s75
	v_sub_u32_e32 v3, v34, v3
	v_add_u32_e32 v35, 0x200, v2
	v_add3_u32 v104, v3, s5, v6
	v_mul_hi_u32 v3, v35, s87
	v_lshrrev_b32_e32 v3, 6, v3
	v_mul_lo_u32 v12, v3, s86
	v_mul_lo_u32 v3, v3, s75
	v_sub_u32_e32 v3, v35, v3
	v_add_u32_e32 v36, 0x300, v2
	v_add3_u32 v106, v3, s5, v12
	v_mul_hi_u32 v3, v36, s87
	v_lshrrev_b32_e32 v3, 6, v3
	v_mul_lo_u32 v14, v3, s86
	v_mul_lo_u32 v3, v3, s75
	v_sub_u32_e32 v3, v36, v3
	v_add_u32_e32 v37, 0x400, v2
	v_add3_u32 v108, v3, s5, v14
	v_mul_hi_u32 v3, v37, s87
	v_lshrrev_b32_e32 v3, 6, v3
	v_mul_lo_u32 v16, v3, s86
	v_mul_lo_u32 v3, v3, s75
	v_sub_u32_e32 v3, v37, v3
	v_add_u32_e32 v38, 0x500, v2
	v_add3_u32 v110, v3, s5, v16
	v_mul_hi_u32 v3, v38, s87
	v_lshrrev_b32_e32 v3, 6, v3
	v_mul_lo_u32 v18, v3, s86
	v_mul_lo_u32 v3, v3, s75
	v_sub_u32_e32 v3, v38, v3
	v_add_u32_e32 v39, 0x600, v2
	v_add3_u32 v112, v3, s5, v18
	v_mul_hi_u32 v3, v39, s87
	v_lshrrev_b32_e32 v3, 6, v3
	v_mul_lo_u32 v20, v3, s86
	v_mul_lo_u32 v3, v3, s75
	v_sub_u32_e32 v3, v39, v3
	v_add_u32_e32 v40, 0x700, v2
	v_add3_u32 v114, v3, s5, v20
	v_mul_hi_u32 v3, v40, s87
	v_lshrrev_b32_e32 v3, 6, v3
	v_mul_lo_u32 v22, v3, s86
	v_mul_lo_u32 v3, v3, s75
	v_mov_b32_e32 v103, v179
	v_mov_b32_e32 v111, v179
	v_sub_u32_e32 v3, v40, v3
	v_lshl_add_u64 v[4:5], v[102:103], 1, s[12:13]
	v_mov_b32_e32 v105, v179
	v_mov_b32_e32 v107, v179
	v_mov_b32_e32 v109, v179
	v_lshl_add_u64 v[16:17], v[110:111], 1, s[12:13]
	v_mov_b32_e32 v113, v179
	v_mov_b32_e32 v115, v179
	v_add3_u32 v116, v3, s5, v22
	v_mov_b32_e32 v117, v179
	v_lshl_add_u64 v[6:7], v[104:105], 1, s[12:13]
	v_lshl_add_u64 v[12:13], v[106:107], 1, s[12:13]
	v_lshl_add_u64 v[14:15], v[108:109], 1, s[12:13]
	v_lshl_add_u64 v[18:19], v[112:113], 1, s[12:13]
	v_lshl_add_u64 v[20:21], v[114:115], 1, s[12:13]
	v_lshl_add_u64 v[22:23], v[116:117], 1, s[12:13]
	global_load_ushort v187, v[20:21], off
	global_load_ushort v188, v[22:23], off
	v_add_u32_e32 v16, 0x800, v2
	v_mul_hi_u32 v3, v16, s87
	v_lshrrev_b32_e32 v3, 6, v3
	v_mul_lo_u32 v4, v3, s86
	v_mul_lo_u32 v3, v3, s75
	v_sub_u32_e32 v3, v16, v3
	v_add_u32_e32 v17, 0x900, v2
	v_add3_u32 v118, v3, s5, v4
	v_mul_hi_u32 v3, v17, s87
	v_lshrrev_b32_e32 v3, 6, v3
	v_mul_lo_u32 v6, v3, s86
	v_mul_lo_u32 v3, v3, s75
	v_sub_u32_e32 v3, v17, v3
	v_add_u32_e32 v18, 0xa00, v2
	v_add3_u32 v120, v3, s5, v6
	v_mul_hi_u32 v3, v18, s87
	v_lshrrev_b32_e32 v3, 6, v3
	v_mul_lo_u32 v12, v3, s86
	v_mul_lo_u32 v3, v3, s75
	v_sub_u32_e32 v3, v18, v3
	v_add_u32_e32 v19, 0xb00, v2
	v_add3_u32 v122, v3, s5, v12
	v_mul_hi_u32 v3, v19, s87
	v_lshrrev_b32_e32 v3, 6, v3
	v_mul_lo_u32 v14, v3, s86
	v_mul_lo_u32 v3, v3, s75
	s_lshl_b64 s[10:11], s[54:55], 17
	s_lshl_b64 s[52:53], s[54:55], 11
	v_mov_b32_e32 v119, v179
	v_sub_u32_e32 v3, v19, v3
	v_lshl_add_u64 v[4:5], v[118:119], 1, s[12:13]
	v_mov_b32_e32 v121, v179
	v_mov_b32_e32 v123, v179
	v_add3_u32 v124, v3, s5, v14
	v_mov_b32_e32 v125, v179
	s_add_u32 s10, s56, s10
	v_ashrrev_i32_e32 v3, 31, v2
	v_lshl_add_u64 v[6:7], v[120:121], 1, s[12:13]
	v_lshl_add_u64 v[12:13], v[122:123], 1, s[12:13]
	v_lshl_add_u64 v[14:15], v[124:125], 1, s[12:13]
	global_load_ushort v189, v[4:5], off
	global_load_ushort v190, v[6:7], off
	global_load_ushort v191, v[12:13], off
	global_load_ushort v192, v[14:15], off
	s_addc_u32 s11, s57, s11
	v_lshlrev_b64 v[4:5], 2, v[2:3]
	v_add_u32_e32 v3, 47, v2
	v_lshl_add_u64 v[6:7], s[10:11], 0, v[4:5]
	v_lshlrev_b32_e32 v126, 2, v0
	v_cmp_gt_u32_e64 s[16:17], s67, v3
	v_and_b32_e32 v3, 0x7ffffff3, v0
	v_and_b32_e32 v1, 31, v2
	v_bfe_u32 v11, v2, 5, 1
	global_load_dword v193, v[6:7], off
	global_load_dword v194, v[6:7], off offset:1024
	v_and_b32_e32 v6, 16, v126
	v_lshlrev_b32_e32 v3, 1, v3
	v_and_b32_e32 v7, 8, v0
	v_ashrrev_i32_e32 v24, 6, v2
	s_movk_i32 s5, 0x8f
	v_or3_b32 v3, v6, v3, v7
	v_mul_u32_u24_e32 v6, 56, v1
	v_lshlrev_b32_e32 v128, 4, v11
	v_cmp_lt_i32_e64 s[14:15], s5, v2
	s_movk_i32 s5, 0x4c
	v_lshl_add_u32 v145, v6, 1, v128
	v_lshlrev_b32_e32 v6, 5, v24
	v_ashrrev_i32_e32 v9, 4, v9
	s_waitcnt vmcnt(30)
	v_mad_u64_u32 v[12:13], s[18:19], v0, s5, v[126:127]
	v_or_b32_e32 v7, v6, v1
	v_add_u32_e32 v9, v9, v10
	v_mad_u64_u32 v[130:131], s[18:19], v7, s74, v[128:129]
	v_lshlrev_b32_e32 v13, 5, v1
	v_mul_lo_u32 v10, v9, s75
	v_cmp_lt_i32_e64 s[10:11], 47, v2
	v_cmp_lt_i32_e64 s[12:13], s67, v2
	v_sub_u32_e32 v131, v145, v13
	v_sub_u32_e32 v2, v2, v10
	v_and_b32_e32 v10, 0x7ffffff3, v9
	v_lshlrev_b32_e32 v13, 2, v9
	v_mul_lo_u32 v2, v2, s74
	v_and_b32_e32 v13, 16, v13
	v_lshlrev_b32_e32 v10, 1, v10
	v_add3_u32 v2, v2, v13, v10
	v_and_or_b32 v146, v9, 8, v2
	v_mul_hi_i32 v2, v34, s79
	v_lshrrev_b32_e32 v9, 31, v2
	v_ashrrev_i32_e32 v2, 4, v2
	v_add_u32_e32 v2, v2, v9
	v_mul_lo_u32 v9, v2, s75
	v_sub_u32_e32 v9, v34, v9
	v_and_b32_e32 v10, 0x7ffffff3, v2
	v_lshlrev_b32_e32 v13, 2, v2
	v_mul_lo_u32 v9, v9, s74
	v_and_b32_e32 v13, 16, v13
	v_lshlrev_b32_e32 v10, 1, v10
	v_add3_u32 v9, v9, v13, v10
	v_and_or_b32 v148, v2, 8, v9
	v_mul_hi_i32 v2, v35, s79
	v_lshrrev_b32_e32 v9, 31, v2
	v_ashrrev_i32_e32 v2, 4, v2
	v_add_u32_e32 v2, v2, v9
	v_mul_lo_u32 v9, v2, s75
	v_sub_u32_e32 v9, v35, v9
	v_and_b32_e32 v10, 0x7ffffff3, v2
	v_lshlrev_b32_e32 v13, 2, v2
	v_mul_lo_u32 v9, v9, s74
	v_and_b32_e32 v13, 16, v13
	v_lshlrev_b32_e32 v10, 1, v10
	v_add3_u32 v9, v9, v13, v10
	v_and_or_b32 v149, v2, 8, v9
	v_mul_hi_i32 v2, v36, s79
	v_lshrrev_b32_e32 v9, 31, v2
	v_ashrrev_i32_e32 v2, 4, v2
	v_add_u32_e32 v2, v2, v9
	v_mul_lo_u32 v9, v2, s75
	v_sub_u32_e32 v9, v36, v9
	v_and_b32_e32 v10, 0x7ffffff3, v2
	v_lshlrev_b32_e32 v13, 2, v2
	v_mul_lo_u32 v9, v9, s74
	v_and_b32_e32 v13, 16, v13
	v_lshlrev_b32_e32 v10, 1, v10
	v_add3_u32 v9, v9, v13, v10
	v_and_or_b32 v150, v2, 8, v9
	v_mul_hi_i32 v2, v37, s79
	v_lshrrev_b32_e32 v9, 31, v2
	v_ashrrev_i32_e32 v2, 4, v2
	v_add_u32_e32 v2, v2, v9
	v_mul_lo_u32 v9, v2, s75
	v_sub_u32_e32 v9, v37, v9
	v_and_b32_e32 v10, 0x7ffffff3, v2
	v_lshlrev_b32_e32 v13, 2, v2
	v_mul_lo_u32 v9, v9, s74
	v_and_b32_e32 v13, 16, v13
	v_lshlrev_b32_e32 v10, 1, v10
	v_add3_u32 v9, v9, v13, v10
	v_and_or_b32 v151, v2, 8, v9
	v_mul_hi_i32 v2, v38, s79
	v_lshrrev_b32_e32 v9, 31, v2
	v_ashrrev_i32_e32 v2, 4, v2
	v_add_u32_e32 v2, v2, v9
	v_mul_lo_u32 v9, v2, s75
	v_sub_u32_e32 v9, v38, v9
	v_and_b32_e32 v10, 0x7ffffff3, v2
	v_lshlrev_b32_e32 v13, 2, v2
	v_mul_lo_u32 v9, v9, s74
	v_and_b32_e32 v13, 16, v13
	v_lshlrev_b32_e32 v10, 1, v10
	v_add3_u32 v9, v9, v13, v10
	v_and_or_b32 v152, v2, 8, v9
	v_mul_hi_i32 v2, v39, s79
	v_lshrrev_b32_e32 v9, 31, v2
	v_ashrrev_i32_e32 v2, 4, v2
	v_add_u32_e32 v2, v2, v9
	v_mul_lo_u32 v9, v2, s75
	v_sub_u32_e32 v9, v39, v9
	v_and_b32_e32 v10, 0x7ffffff3, v2
	v_lshlrev_b32_e32 v13, 2, v2
	v_mul_lo_u32 v9, v9, s74
	v_and_b32_e32 v13, 16, v13
	v_lshlrev_b32_e32 v10, 1, v10
	v_add3_u32 v9, v9, v13, v10
	v_and_or_b32 v153, v2, 8, v9
	v_mul_hi_i32 v2, v40, s79
	v_lshrrev_b32_e32 v9, 31, v2
	v_ashrrev_i32_e32 v2, 4, v2
	v_add_u32_e32 v2, v2, v9
	v_mul_lo_u32 v9, v2, s75
	v_sub_u32_e32 v9, v40, v9
	v_and_b32_e32 v10, 0x7ffffff3, v2
	v_lshlrev_b32_e32 v13, 2, v2
	v_mul_lo_u32 v9, v9, s74
	v_and_b32_e32 v13, 16, v13
	v_lshlrev_b32_e32 v10, 1, v10
	v_add3_u32 v9, v9, v13, v10
	v_and_or_b32 v154, v2, 8, v9
	v_mul_hi_i32 v2, v16, s79
	v_lshrrev_b32_e32 v9, 31, v2
	v_ashrrev_i32_e32 v2, 4, v2
	v_add_u32_e32 v2, v2, v9
	v_mul_lo_u32 v9, v2, s75
	v_sub_u32_e32 v9, v16, v9
	v_and_b32_e32 v10, 0x7ffffff3, v2
	v_lshlrev_b32_e32 v13, 2, v2
	v_mul_lo_u32 v9, v9, s74
	v_and_b32_e32 v13, 16, v13
	v_lshlrev_b32_e32 v10, 1, v10
	v_add3_u32 v9, v9, v13, v10
	v_and_or_b32 v155, v2, 8, v9
	v_mul_hi_i32 v2, v17, s79
	v_lshrrev_b32_e32 v9, 31, v2
	v_ashrrev_i32_e32 v2, 4, v2
	v_add_u32_e32 v2, v2, v9
	v_mul_lo_u32 v9, v2, s75
	v_sub_u32_e32 v9, v17, v9
	v_and_b32_e32 v10, 0x7ffffff3, v2
	v_lshlrev_b32_e32 v13, 2, v2
	v_mul_lo_u32 v9, v9, s74
	v_and_b32_e32 v13, 16, v13
	v_lshlrev_b32_e32 v10, 1, v10
	v_add3_u32 v9, v9, v13, v10
	v_and_or_b32 v156, v2, 8, v9
	v_mul_hi_i32 v2, v18, s79
	v_lshrrev_b32_e32 v9, 31, v2
	v_ashrrev_i32_e32 v2, 4, v2
	v_add_u32_e32 v2, v2, v9
	v_mul_lo_u32 v9, v2, s75
	v_sub_u32_e32 v9, v18, v9
	v_and_b32_e32 v10, 0x7ffffff3, v2
	v_lshlrev_b32_e32 v13, 2, v2
	v_mul_lo_u32 v9, v9, s74
	v_and_b32_e32 v13, 16, v13
	v_lshlrev_b32_e32 v10, 1, v10
	v_add3_u32 v9, v9, v13, v10
	v_and_or_b32 v157, v2, 8, v9
	v_mul_hi_i32 v2, v19, s79
	v_lshrrev_b32_e32 v9, 31, v2
	v_ashrrev_i32_e32 v2, 4, v2
	v_add_u32_e32 v2, v2, v9
	v_mul_lo_u32 v9, v2, s75
	v_sub_u32_e32 v9, v19, v9
	v_and_b32_e32 v10, 0x7ffffff3, v2
	v_lshlrev_b32_e32 v13, 2, v2
	v_mul_lo_u32 v9, v9, s74
	v_and_b32_e32 v13, 16, v13
	v_lshlrev_b32_e32 v10, 1, v10
	v_add3_u32 v9, v9, v13, v10
	s_movk_i32 s5, 0x1c0
	v_and_or_b32 v158, v2, 8, v9
	v_mul_lo_u32 v2, v8, s5
	v_add_lshl_u32 v159, v2, v0, 1
	v_lshl_add_u32 v160, v2, 1, v3
	v_lshlrev_b32_e32 v2, 4, v8
	v_lshlrev_b32_e32 v141, 9, v8
	v_and_b32_e32 v2, 0xffffffe0, v2
	v_and_b32_e32 v8, 8, v25
	s_mov_b32 s5, 0x7ffffff1
	v_add3_u32 v161, v12, v2, v8
	v_or_b32_e32 v2, 1, v25
	v_bitop3_b32 v9, v25, s5, 1 bitop3:0xc8
	v_mul_lo_u32 v2, v2, 56
	v_lshlrev_b32_e32 v9, 1, v9
	v_add3_u32 v164, v12, v9, v8
	v_add_u32_e32 v9, 56, v2
	s_mov_b32 s5, 0x7ffffff2
	v_add_lshl_u32 v165, v9, v0, 1
	v_lshl_add_u32 v166, v9, 1, v3
	v_bitop3_b32 v9, v25, s5, 2 bitop3:0xc8
	v_lshlrev_b32_e32 v9, 1, v9
	v_add3_u32 v167, v12, v9, v8
	v_add_u32_e32 v9, 0x70, v2
	s_mov_b32 s5, 0x7ffffff3
	v_add_lshl_u32 v168, v9, v0, 1
	v_lshl_add_u32 v169, v9, 1, v3
	v_bitop3_b32 v9, v25, s5, 3 bitop3:0xc8
	v_lshlrev_b32_e32 v9, 1, v9
	v_add3_u32 v170, v12, v9, v8
	v_add_u32_e32 v8, 0xe0, v2
	v_lshlrev_b32_e32 v11, 2, v11
	v_add_lshl_u32 v162, v2, v0, 1
	v_lshl_add_u32 v163, v2, 1, v3
	v_add_lshl_u32 v171, v8, v0, 1
	v_lshl_add_u32 v172, v8, 1, v3
	v_add_u32_e32 v8, 0x118, v2
	v_add_u32_e32 v2, 0x150, v2
	v_add_lshl_u32 v173, v8, v0, 1
	v_add_lshl_u32 v175, v2, v0, 1
	v_or_b32_e32 v0, 2, v11
	v_cmp_gt_u32_e64 s[22:23], v0, v1
	v_or_b32_e32 v0, 3, v11
	v_cmp_gt_u32_e64 s[24:25], v0, v1
	v_or_b32_e32 v0, 8, v11
	v_cmp_gt_u32_e64 s[26:27], v0, v1
	v_or_b32_e32 v0, 9, v11
	v_cmp_gt_u32_e64 s[28:29], v0, v1
	v_or_b32_e32 v0, 10, v11
	v_cmp_gt_u32_e64 s[30:31], v0, v1
	v_or_b32_e32 v0, 11, v11
	v_cmp_gt_u32_e64 s[34:35], v0, v1
	v_or_b32_e32 v0, 16, v11
	v_cmp_gt_u32_e64 s[36:37], v0, v1
	v_or_b32_e32 v0, 17, v11
	v_cmp_gt_u32_e64 s[38:39], v0, v1
	v_or_b32_e32 v0, 18, v11
	v_cmp_gt_u32_e64 s[40:41], v0, v1
	v_or_b32_e32 v0, 19, v11
	v_cmp_gt_u32_e64 s[42:43], v0, v1
	v_or_b32_e32 v0, 24, v11
	v_cmp_gt_u32_e64 s[44:45], v0, v1
	v_or_b32_e32 v0, 25, v11
	v_cmp_gt_u32_e64 s[46:47], v0, v1
	v_or_b32_e32 v0, 26, v11
	v_cmp_gt_u32_e64 s[48:49], v0, v1
	v_or_b32_e32 v0, 27, v11
	v_lshl_add_u32 v180, v2, 1, v3
	v_cmp_gt_u32_e64 s[50:51], v0, v1
	s_mul_hi_i32 s5, s54, 0x300000
	s_mul_i32 s54, s54, 0x300000
	v_mul_hi_u32_u24_e32 v0, 0x600, v1
	v_mul_u32_u24_e32 v2, 0x600, v1
	v_cmp_gt_u32_e64 s[18:19], v11, v1
	v_cmp_lt_u32_e64 s[20:21], v11, v1
	v_or_b32_e32 v1, s5, v0
	v_or_b32_e32 v0, s54, v2
	v_mad_u64_u32 v[0:1], s[4:5], s4, v231, v[0:1]
	v_ashrrev_i32_e32 v7, 31, v6
	v_or_b32_e32 v0, v0, v128
	v_lshl_add_u64 v[0:1], v[6:7], 2, v[0:1]
	v_lshl_add_u64 v[0:1], s[2:3], 0, v[0:1]
	s_mov_b64 s[2:3], 0x26e22140
	v_mov_b32_e32 v14, v179
	v_mov_b32_e32 v15, v179
	v_cmp_gt_i32_e32 vcc, 3, v24
	v_lshl_add_u32 v174, v8, 1, v3
	s_waitcnt vmcnt(27)
	v_perm_b32 v39, v27, v26, s76
	s_waitcnt vmcnt(23)
	v_perm_b32 v38, v29, v28, s76
	s_waitcnt vmcnt(19)
	v_perm_b32 v37, v31, v30, s76
	v_lshl_add_u64 v[132:133], s[56:57], 0, v[4:5]
	v_lshl_add_u64 v[134:135], v[0:1], 0, s[2:3]
	v_mov_b32_e32 v0, v179
	v_mov_b32_e32 v1, v179
	v_mov_b32_e32 v2, v179
	v_mov_b32_e32 v3, v179
	v_mov_b32_e32 v4, v179
	v_mov_b32_e32 v5, v179
	v_mov_b32_e32 v6, v179
	v_mov_b32_e32 v7, v179
	v_mov_b32_e32 v8, v179
	v_mov_b32_e32 v9, v179
	v_mov_b32_e32 v10, v179
	v_mov_b32_e32 v11, v179
	v_mov_b32_e32 v12, v179
	v_mov_b32_e32 v13, v179
	v_mov_b64_e32 v[30:31], v[14:15]
	s_waitcnt vmcnt(15)
	v_perm_b32 v36, v33, v32, s76
	s_mov_b32 s56, 32
	v_mov_b64_e32 v[28:29], v[12:13]
	v_mov_b64_e32 v[26:27], v[10:11]
	v_mov_b64_e32 v[24:25], v[8:9]
	v_mov_b64_e32 v[22:23], v[6:7]
	v_mov_b64_e32 v[20:21], v[4:5]
	v_mov_b64_e32 v[18:19], v[2:3]
	v_mov_b64_e32 v[16:17], v[0:1]
	v_lshlrev_b32_e32 v73, 1, v72
	v_lshlrev_b32_e32 v75, 1, v74
	v_lshlrev_b32_e32 v77, 1, v76
	v_lshlrev_b32_e32 v79, 1, v78
	v_lshlrev_b32_e32 v81, 1, v80
	v_lshlrev_b32_e32 v83, 1, v82
	v_lshlrev_b32_e32 v85, 1, v84
	v_lshlrev_b32_e32 v87, 1, v86
	v_lshlrev_b32_e32 v89, 1, v88
	v_lshlrev_b32_e32 v91, 1, v90
	v_lshlrev_b32_e32 v93, 1, v92
	v_lshlrev_b32_e32 v95, 1, v94
	v_lshlrev_b32_e32 v97, 1, v96
	v_lshlrev_b32_e32 v99, 1, v98
	v_lshlrev_b32_e32 v101, 1, v100
	v_lshlrev_b32_e32 v103, 1, v102
	v_lshlrev_b32_e32 v105, 1, v104
	v_lshlrev_b32_e32 v107, 1, v106
	v_lshlrev_b32_e32 v109, 1, v108
	v_lshlrev_b32_e32 v111, 1, v110
	v_lshlrev_b32_e32 v113, 1, v112
	v_lshlrev_b32_e32 v115, 1, v114
	v_lshlrev_b32_e32 v117, 1, v116
	v_lshlrev_b32_e32 v119, 1, v118
	v_lshlrev_b32_e32 v121, 1, v120
	v_lshlrev_b32_e32 v123, 1, v122
	v_lshlrev_b32_e32 v125, 1, v124
	s_branch .LBB0_537
.LBB0_536:
	s_or_b64 exec, exec, s[2:3]
	s_add_i32 s56, s56, 32
	s_mov_b64 s[2:3], 0xc000
	s_waitcnt vmcnt(21)
	v_perm_b32 v39, v196, v195, s76
	s_waitcnt vmcnt(17)
	v_perm_b32 v38, v198, v197, s76
	s_waitcnt vmcnt(13)
	v_perm_b32 v37, v200, v199, s76
	s_waitcnt vmcnt(9)
	v_perm_b32 v36, v202, v201, s76
	s_cmpk_lg_i32 s56, 0x820
	v_lshl_add_u64 v[134:135], v[134:135], 0, s[2:3]
	s_barrier
	s_cbranch_scc0 .LBB0_430
.LBB0_537:
	v_mov_b32_e32 v40, 0
	v_mov_b32_e32 v41, 0
	v_mov_b32_e32 v42, 0
	v_mov_b32_e32 v43, 0
	v_mov_b32_e32 v44, 0
	v_mov_b32_e32 v45, 0
	v_mov_b32_e32 v46, 0
	v_mov_b32_e32 v47, 0
	s_waitcnt vmcnt(0)
	ds_write2st64_b32 v129, v193, v194 offset0:96 offset1:100
	ds_write_b16 v246, v181 offset:15872
	ds_write_b16_d16_hi v246, v181 offset:15952
	ds_write_b16 v247, v182 offset:15872
	ds_write_b16_d16_hi v247, v182 offset:15952
	ds_write_b16 v248, v183 offset:15872
	ds_write_b16_d16_hi v248, v183 offset:15952
	ds_write_b16 v249, v184 offset:15872
	ds_write_b16_d16_hi v249, v184 offset:15952
	ds_write_b16 v250, v185 offset:15872
	ds_write_b16_d16_hi v250, v185 offset:15952
	ds_write_b16 v251, v186 offset:15872
	ds_write_b16_d16_hi v251, v186 offset:15952
	s_waitcnt lgkmcnt(0)
	s_barrier
	s_and_saveexec_b64 s[2:3], s[8:9]
	s_cbranch_execz .LBB0_539
	s_mov_b32 s4, 0xbd800000
	ds_read_b128 v[32:35], v141 offset:24576
	ds_read_b128 v[48:51], v141 offset:24592
	ds_read_b128 v[182:185], v141 offset:24608
	ds_read_b128 v[186:189], v141 offset:24624
	ds_read_b128 v[190:193], v141 offset:24640
	ds_read_b128 v[194:197], v141 offset:24656
	s_waitcnt lgkmcnt(4)
	v_fma_f32 v52, v32, v58, v127
	v_mul_f32_e32 v53, v33, v56
	v_fmac_f32_e32 v52, v34, v62
	v_fmac_f32_e32 v53, v35, v60
	v_fmac_f32_e32 v52, v48, v59
	v_fmac_f32_e32 v53, v49, v57
	v_fmac_f32_e32 v52, v50, v63
	v_fmac_f32_e32 v53, v51, v61
	ds_read_b128 v[32:35], v141 offset:24672
	ds_read_b128 v[48:51], v141 offset:24688
	s_waitcnt lgkmcnt(4)
	v_fmac_f32_e32 v52, v182, v66
	v_fmac_f32_e32 v53, v183, v64
	v_fmac_f32_e32 v52, v184, v70
	v_fmac_f32_e32 v53, v185, v68
	v_fmac_f32_e32 v52, v186, v67
	v_fmac_f32_e32 v53, v187, v65
	v_fmac_f32_e32 v52, v188, v71
	v_fmac_f32_e32 v53, v189, v69
	ds_read_b128 v[182:185], v141 offset:24704
	ds_read_b128 v[186:189], v141 offset:24720
	v_add_f32_e32 v200, v52, v53
	v_mul_f32_e32 v200, 0xbfb8aa3b, v200
	v_exp_f32_e32 v200, v200
	s_waitcnt lgkmcnt(4)
	v_fma_f32 v198, v190, v58, v127
	v_mul_f32_e32 v199, v191, v56
	v_fmac_f32_e32 v198, v192, v62
	v_fmac_f32_e32 v199, v193, v60
	v_fmac_f32_e32 v198, v194, v59
	v_fmac_f32_e32 v199, v195, v57
	v_fmac_f32_e32 v198, v196, v63
	v_fmac_f32_e32 v199, v197, v61
	ds_read_b128 v[190:193], v141 offset:24736
	ds_read_b128 v[194:197], v141 offset:24752
	v_add_f32_e32 v200, 1.0, v200
	v_log_f32_e32 v200, v200
	s_waitcnt lgkmcnt(4)
	v_fmac_f32_e32 v198, v32, v66
	v_fmac_f32_e32 v199, v33, v64
	v_fmac_f32_e32 v198, v34, v70
	v_fmac_f32_e32 v199, v35, v68
	v_fmac_f32_e32 v198, v48, v67
	v_fmac_f32_e32 v199, v49, v65
	v_fmac_f32_e32 v198, v50, v71
	v_fmac_f32_e32 v199, v51, v69
	ds_read_b128 v[32:35], v141 offset:24768
	ds_read_b128 v[48:51], v141 offset:24784
	v_mul_f32_e32 v40, 0xbd800000, v200
	v_add_f32_e32 v201, v198, v199
	v_mul_f32_e32 v201, 0xbfb8aa3b, v201
	v_exp_f32_e32 v201, v201
	s_waitcnt lgkmcnt(4)
	v_fma_f32 v52, v182, v58, v127
	v_mul_f32_e32 v53, v183, v56
	v_fmac_f32_e32 v52, v184, v62
	v_fmac_f32_e32 v53, v185, v60
	v_fmac_f32_e32 v52, v186, v59
	v_fmac_f32_e32 v53, v187, v57
	v_fmac_f32_e32 v52, v188, v63
	v_fmac_f32_e32 v53, v189, v61
	ds_read_b128 v[182:185], v141 offset:24800
	ds_read_b128 v[186:189], v141 offset:24816
	v_add_f32_e32 v201, 1.0, v201
	v_log_f32_e32 v201, v201
	s_waitcnt lgkmcnt(4)
	v_fmac_f32_e32 v52, v190, v66
	v_fmac_f32_e32 v53, v191, v64
	v_fmac_f32_e32 v52, v192, v70
	v_fmac_f32_e32 v53, v193, v68
	v_fmac_f32_e32 v52, v194, v67
	v_fmac_f32_e32 v53, v195, v65
	v_fmac_f32_e32 v52, v196, v71
	v_fmac_f32_e32 v53, v197, v69
	ds_read_b128 v[190:193], v141 offset:24832
	ds_read_b128 v[194:197], v141 offset:24848
	v_fmamk_f32 v41, v201, 0xbd800000, v40
	v_add_f32_e32 v200, v52, v53
	v_mul_f32_e32 v200, 0xbfb8aa3b, v200
	v_exp_f32_e32 v200, v200
	s_waitcnt lgkmcnt(4)
	v_fma_f32 v198, v32, v58, v127
	v_mul_f32_e32 v199, v33, v56
	v_fmac_f32_e32 v198, v34, v62
	v_fmac_f32_e32 v199, v35, v60
	v_fmac_f32_e32 v198, v48, v59
	v_fmac_f32_e32 v199, v49, v57
	v_fmac_f32_e32 v198, v50, v63
	v_fmac_f32_e32 v199, v51, v61
	ds_read_b128 v[32:35], v141 offset:24864
	ds_read_b128 v[48:51], v141 offset:24880
	v_add_f32_e32 v200, 1.0, v200
	v_log_f32_e32 v200, v200
	s_waitcnt lgkmcnt(4)
	v_fmac_f32_e32 v198, v182, v66
	v_fmac_f32_e32 v199, v183, v64
	v_fmac_f32_e32 v198, v184, v70
	v_fmac_f32_e32 v199, v185, v68
	v_fmac_f32_e32 v198, v186, v67
	v_fmac_f32_e32 v199, v187, v65
	v_fmac_f32_e32 v198, v188, v71
	v_fmac_f32_e32 v199, v189, v69
	ds_read_b128 v[182:185], v141 offset:24896
	ds_read_b128 v[186:189], v141 offset:24912
	v_fmamk_f32 v42, v200, 0xbd800000, v41
	v_add_f32_e32 v201, v198, v199
	v_mul_f32_e32 v201, 0xbfb8aa3b, v201
	v_exp_f32_e32 v201, v201
	s_waitcnt lgkmcnt(4)
	v_fma_f32 v52, v190, v58, v127
	v_mul_f32_e32 v53, v191, v56
	v_fmac_f32_e32 v52, v192, v62
	v_fmac_f32_e32 v53, v193, v60
	v_fmac_f32_e32 v52, v194, v59
	v_fmac_f32_e32 v53, v195, v57
	v_fmac_f32_e32 v52, v196, v63
	v_fmac_f32_e32 v53, v197, v61
	ds_read_b128 v[190:193], v141 offset:24928
	ds_read_b128 v[194:197], v141 offset:24944
	v_add_f32_e32 v201, 1.0, v201
	v_log_f32_e32 v201, v201
	s_waitcnt lgkmcnt(4)
	v_fmac_f32_e32 v52, v32, v66
	v_fmac_f32_e32 v53, v33, v64
	v_fmac_f32_e32 v52, v34, v70
	v_fmac_f32_e32 v53, v35, v68
	v_fmac_f32_e32 v52, v48, v67
	v_fmac_f32_e32 v53, v49, v65
	v_fmac_f32_e32 v52, v50, v71
	v_fmac_f32_e32 v53, v51, v69
	ds_read_b128 v[32:35], v141 offset:24960
	ds_read_b128 v[48:51], v141 offset:24976
	v_fmamk_f32 v43, v201, 0xbd800000, v42
	v_add_f32_e32 v200, v52, v53
	v_mul_f32_e32 v200, 0xbfb8aa3b, v200
	v_exp_f32_e32 v200, v200
	s_waitcnt lgkmcnt(4)
	v_fma_f32 v198, v182, v58, v127
	v_mul_f32_e32 v199, v183, v56
	v_fmac_f32_e32 v198, v184, v62
	v_fmac_f32_e32 v199, v185, v60
	v_fmac_f32_e32 v198, v186, v59
	v_fmac_f32_e32 v199, v187, v57
	v_fmac_f32_e32 v198, v188, v63
	v_fmac_f32_e32 v199, v189, v61
	ds_read_b128 v[182:185], v141 offset:24992
	ds_read_b128 v[186:189], v141 offset:25008
	v_add_f32_e32 v200, 1.0, v200
	v_log_f32_e32 v200, v200
	s_waitcnt lgkmcnt(4)
	v_fmac_f32_e32 v198, v190, v66
	v_fmac_f32_e32 v199, v191, v64
	v_fmac_f32_e32 v198, v192, v70
	v_fmac_f32_e32 v199, v193, v68
	v_fmac_f32_e32 v198, v194, v67
	v_fmac_f32_e32 v199, v195, v65
	v_fmac_f32_e32 v198, v196, v71
	v_fmac_f32_e32 v199, v197, v69
	ds_read_b128 v[190:193], v141 offset:25024
	ds_read_b128 v[194:197], v141 offset:25040
	v_fmamk_f32 v44, v200, 0xbd800000, v43
	v_add_f32_e32 v201, v198, v199
	v_mul_f32_e32 v201, 0xbfb8aa3b, v201
	v_exp_f32_e32 v201, v201
	s_waitcnt lgkmcnt(4)
	v_fma_f32 v52, v32, v58, v127
	v_mul_f32_e32 v53, v33, v56
	v_fmac_f32_e32 v52, v34, v62
	v_fmac_f32_e32 v53, v35, v60
	v_fmac_f32_e32 v52, v48, v59
	v_fmac_f32_e32 v53, v49, v57
	v_fmac_f32_e32 v52, v50, v63
	v_fmac_f32_e32 v53, v51, v61
	ds_read_b128 v[32:35], v141 offset:25056
	ds_read_b128 v[48:51], v141 offset:25072
	v_add_f32_e32 v201, 1.0, v201
	v_log_f32_e32 v201, v201
	s_waitcnt lgkmcnt(4)
	v_fmac_f32_e32 v52, v182, v66
	v_fmac_f32_e32 v53, v183, v64
	v_fmac_f32_e32 v52, v184, v70
	v_fmac_f32_e32 v53, v185, v68
	v_fmac_f32_e32 v52, v186, v67
	v_fmac_f32_e32 v53, v187, v65
	v_fmac_f32_e32 v52, v188, v71
	v_fmac_f32_e32 v53, v189, v69
	v_fmamk_f32 v45, v201, 0xbd800000, v44
	v_add_f32_e32 v200, v52, v53
	v_mul_f32_e32 v200, 0xbfb8aa3b, v200
	v_exp_f32_e32 v200, v200
	s_waitcnt lgkmcnt(2)
	v_fma_f32 v198, v190, v58, v127
	v_mul_f32_e32 v199, v191, v56
	v_fmac_f32_e32 v198, v192, v62
	v_fmac_f32_e32 v199, v193, v60
	v_fmac_f32_e32 v198, v194, v59
	v_fmac_f32_e32 v199, v195, v57
	v_fmac_f32_e32 v198, v196, v63
	v_fmac_f32_e32 v199, v197, v61
	v_add_f32_e32 v200, 1.0, v200
	v_log_f32_e32 v200, v200
	s_waitcnt lgkmcnt(0)
	v_fmac_f32_e32 v198, v32, v66
	v_fmac_f32_e32 v199, v33, v64
	v_fmac_f32_e32 v198, v34, v70
	v_fmac_f32_e32 v199, v35, v68
	v_fmac_f32_e32 v198, v48, v67
	v_fmac_f32_e32 v199, v49, v65
	v_fmac_f32_e32 v198, v50, v71
	v_fmac_f32_e32 v199, v51, v69
	v_fmamk_f32 v46, v200, 0xbd800000, v45
	v_add_f32_e32 v201, v198, v199
	v_mul_f32_e32 v201, 0xbfb8aa3b, v201
	v_exp_f32_e32 v201, v201
	s_nop 0
	v_add_f32_e32 v201, 1.0, v201
	v_log_f32_e32 v201, v201
	s_nop 0
	v_fmamk_f32 v47, v201, 0xbd800000, v46
	ds_write_b32 v129, v47 offset:23808

.LBB0_543:
	s_or_b64 exec, exec, s[2:3]
	s_cmpk_lg_i32 s56, 0x800
	s_cselect_b32 s2, s56, 0x7e0
	s_add_u32 s2, s52, s2
	s_addc_u32 s3, s53, 0
	s_mul_i32 s4, s3, 0x900
	s_mul_hi_u32 s5, s2, 0x900
	s_add_i32 s5, s5, s4
	s_mul_i32 s4, s2, 0x900
	s_add_u32 s54, s58, s4
	s_addc_u32 s55, s59, s5
	v_lshl_add_u64 v[32:33], v[178:179], 1, s[54:55]
	s_waitcnt lgkmcnt(0)
	s_barrier
	global_load_ushort v195, v[32:33], off
	global_load_ushort v143, v73, s[54:55]
	global_load_ushort v196, v75, s[54:55]
	global_load_ushort v140, v77, s[54:55]
	global_load_ushort v197, v79, s[54:55]
	global_load_ushort v136, v81, s[54:55]
	global_load_ushort v198, v83, s[54:55]
	global_load_ushort v138, v85, s[54:55]
	global_load_ushort v199, v87, s[54:55]
	global_load_ushort v144, v89, s[54:55]
	global_load_ushort v200, v91, s[54:55]
	global_load_ushort v142, v93, s[54:55]
	global_load_ushort v201, v95, s[54:55]
	global_load_ushort v137, v97, s[54:55]
	global_load_ushort v202, v99, s[54:55]
	global_load_ushort v139, v101, s[54:55]
	global_load_dword v181, v240, s[54:55]
	global_load_dword v182, v241, s[54:55]
	global_load_dword v183, v242, s[54:55]
	global_load_dword v184, v243, s[54:55]
	global_load_dword v185, v244, s[54:55]
	global_load_dword v186, v245, s[54:55]
	s_lshl_b64 s[2:3], s[2:3], 6
	v_lshl_add_u64 v[32:33], v[132:133], 0, s[2:3]
	global_load_dword v193, v[32:33], off
	global_load_dword v194, v[32:33], off offset:1024
	s_and_saveexec_b64 s[2:3], vcc
	s_cbranch_execz .LBB0_536
	ds_read_b128 v[32:35], v145 offset:7168
	ds_read_b128 v[36:39], v145
	ds_read_b128 v[48:51], v145 offset:32
	ds_read_b128 v[52:55], v145 offset:7200
	v_cvt_pk_bf16_f32 v208, v8, v9
	v_cvt_pk_bf16_f32 v209, v10, v11
	s_waitcnt lgkmcnt(2)
	v_mfma_f32_32x32x16_bf16 v[32:47], v[32:35], v[36:39], 0
	v_cvt_pk_bf16_f32 v210, v12, v13
	v_cvt_pk_bf16_f32 v211, v14, v15
	v_cvt_pk_bf16_f32 v212, v16, v17
	v_cvt_pk_bf16_f32 v213, v18, v19
	v_cvt_pk_bf16_f32 v214, v20, v21
	v_cvt_pk_bf16_f32 v215, v22, v23
	s_waitcnt lgkmcnt(0)
	v_mfma_f32_32x32x16_bf16 v[32:47], v[52:55], v[48:51], v[32:47]
	ds_read_b128 v[48:51], v145 offset:7232
	ds_read_b128 v[52:55], v145 offset:64
	s_waitcnt lgkmcnt(0)
	v_mfma_f32_32x32x16_bf16 v[32:47], v[48:51], v[52:55], v[32:47]
	ds_read_b128 v[52:55], v130 offset:15872
	ds_read_b128 v[48:51], v130 offset:15904
	ds_read_b128 v[236:239], v145 offset:3584
	s_nop 8
	v_cndmask_b32_e64 v32, v32, 0, s[18:19]
	v_cndmask_b32_e64 v33, 0, v33, s[20:21]
	v_cndmask_b32_e64 v34, v34, 0, s[22:23]
	v_cndmask_b32_e64 v35, v35, 0, s[24:25]
	v_cndmask_b32_e64 v36, v36, 0, s[26:27]
	v_cndmask_b32_e64 v37, v37, 0, s[28:29]
	v_cndmask_b32_e64 v38, v38, 0, s[30:31]
	v_cndmask_b32_e64 v39, v39, 0, s[34:35]
	v_cndmask_b32_e64 v40, v40, 0, s[36:37]
	v_cndmask_b32_e64 v41, v41, 0, s[38:39]
	v_cndmask_b32_e64 v42, v42, 0, s[40:41]
	v_cndmask_b32_e64 v43, v43, 0, s[42:43]
	v_cndmask_b32_e64 v44, v44, 0, s[44:45]
	v_cndmask_b32_e64 v45, v45, 0, s[46:47]
	v_cndmask_b32_e64 v46, v46, 0, s[48:49]
	v_cndmask_b32_e64 v47, v47, 0, s[50:51]
	v_cvt_pk_bf16_f32 v32, v32, v33
	v_cvt_pk_bf16_f32 v33, v34, v35
	v_cvt_pk_bf16_f32 v34, v36, v37
	v_cvt_pk_bf16_f32 v35, v38, v39
	v_cvt_pk_bf16_f32 v204, v40, v41
	v_cvt_pk_bf16_f32 v205, v42, v43
	v_cvt_pk_bf16_f32 v206, v44, v45
	v_cvt_pk_bf16_f32 v207, v46, v47
	s_waitcnt lgkmcnt(2)
	v_mfma_f32_32x32x16_bf16 v[32:47], v[52:55], v[32:35], 0
	s_waitcnt lgkmcnt(1)
	v_mfma_f32_32x32x16_bf16 v[32:47], v[48:51], v[204:207], v[32:47]
	v_cvt_pk_bf16_f32 v204, v0, v1
	v_cvt_pk_bf16_f32 v205, v2, v3
	v_cvt_pk_bf16_f32 v206, v4, v5
	v_cvt_pk_bf16_f32 v207, v6, v7
	s_waitcnt lgkmcnt(0)
	s_nop 0
	v_mfma_f32_32x32x16_bf16 v[32:47], v[204:207], v[236:239], v[32:47]
	ds_read_b128 v[204:207], v145 offset:3616
	s_waitcnt lgkmcnt(0)
	v_mfma_f32_32x32x16_bf16 v[32:47], v[208:211], v[204:207], v[32:47]
	ds_read_b128 v[204:207], v145 offset:3648
	s_waitcnt lgkmcnt(0)
	v_mfma_f32_32x32x16_bf16 v[32:47], v[212:215], v[204:207], v[32:47]
	s_nop 11
	global_store_dwordx4 v[134:135], v[32:35], off offset:-64
	global_store_dwordx4 v[134:135], v[36:39], off offset:-32
	global_store_dwordx4 v[134:135], v[40:43], off
	global_store_dwordx4 v[134:135], v[44:47], off offset:32
	ds_read_b128 v[32:35], v128 offset:23680
	ds_read_b128 v[36:39], v128 offset:23552
	ds_read_b128 v[40:43], v128 offset:23584
	ds_read_b128 v[44:47], v128 offset:23712
	ds_read_b128 v[204:207], v128 offset:23616
	ds_read_b128 v[208:211], v128 offset:23744
	ds_read_b128 v[212:215], v128 offset:23648
	ds_read_b128 v[236:239], v128 offset:23776
	s_waitcnt lgkmcnt(6)
	v_pk_mul_f32 v[2:3], v[2:3], v[38:39]
	v_pk_mul_f32 v[0:1], v[0:1], v[36:37]
	v_pk_mul_f32 v[18:19], v[18:19], v[34:35]
	v_pk_mul_f32 v[16:17], v[16:17], v[32:33]
	ds_read_b128 v[32:35], v131 offset:10752
	ds_read_b128 v[36:39], v131 offset:10784
	s_waitcnt lgkmcnt(3)
	v_pk_mul_f32 v[14:15], v[14:15], v[214:215]
	v_pk_mul_f32 v[10:11], v[10:11], v[206:207]
	v_pk_mul_f32 v[6:7], v[6:7], v[42:43]
	v_pk_mul_f32 v[12:13], v[12:13], v[212:213]
	v_pk_mul_f32 v[8:9], v[8:9], v[204:205]
	v_pk_mul_f32 v[4:5], v[4:5], v[40:41]
	s_waitcnt lgkmcnt(2)
	v_pk_mul_f32 v[30:31], v[30:31], v[238:239]
	v_pk_mul_f32 v[26:27], v[26:27], v[210:211]
	s_waitcnt lgkmcnt(1)
	v_mfma_f32_32x32x16_bf16 v[0:15], v[32:35], v[52:55], v[0:15]
	ds_read_b128 v[32:35], v131 offset:13312
	v_mul_f32_e64 v22, v22, v46
	v_mul_f32_e64 v23, v23, v47
	v_mul_f32_e64 v28, v28, v236
	v_mul_f32_e64 v29, v29, v237
	v_pk_mul_f32 v[24:25], v[24:25], v[208:209]
	v_pk_mul_f32 v[20:21], v[20:21], v[44:45]
	s_waitcnt lgkmcnt(0)
	s_nop 0
	v_mfma_f32_32x32x16_bf16 v[16:31], v[32:35], v[52:55], v[16:31]
	ds_read_b128 v[32:35], v131 offset:13344
	v_mfma_f32_32x32x16_bf16 v[0:15], v[36:39], v[48:51], v[0:15]
	s_waitcnt lgkmcnt(0)
	v_mfma_f32_32x32x16_bf16 v[16:31], v[32:35], v[48:51], v[16:31]
	s_branch .LBB0_536
